# v4 + attention: waves 4-7 start each key tile ~1000 cycles later (s_sleep stagger of the two SIMD-partner wave groups)
# baseline (speedup 1.0000x reference)
; #define LAS __attribute__((address_space(3)))
; __device__ __forceinline__ void attn_stage(LAS unsigned char* lds, int buf, const bf16_t* kbase, const bf16_t* vbase, int k0, int wid, int lane) {
;     ...
;     } else {
; #pragma unroll
;         for (int j = 0; j < 8; ++j) {
;             const int pi = wid * 8 + j, row = (pi - 32) * 8 + (lane >> 3), gch = (lane & 7) ^ ((row >> 1) & 7);
;             const bf16_t* src = vbase + (size_t)row * MTOK + k0 + gch * 8;
;             __builtin_amdgcn_global_load_lds((const unsigned*)src, (LAS unsigned*)(lds + buf * 65536 + pi * 1024), 16, 0, 0);
;         }
; __device__ __forceinline__ void attn_phase(LAS unsigned char* lds, const KArgs& P, int G, int c, int wv) {
;     ...
;         for (int kt = kt0; kt < nkt; ++kt) {
;             asm volatile("s_waitcnt vmcnt(0)" ::: "memory");
;             __syncthreads();
;             int lz = lane; asm volatile("" : "+v"(lz));
;             if (kt + 1 < nkt) attn_stage(lds, (kt + 1) & 1, kbase, vbase, (kt + 1) * 64, wid, lz);
.LBB0_359:
	s_add_i32 s69, s69, 1
	s_waitcnt vmcnt(0)
	s_cmp_ge_u32 s69, s12
	s_cselect_b64 s[74:75], -1, 0
	v_mov_b32_e32 v130, v246
	s_and_b64 vcc, exec, s[74:75]
	s_waitcnt lgkmcnt(0)
	s_barrier
	s_cmp_eq_u64 s[18:19], 0
	s_cbranch_scc0 .Lattn_nosleep
	s_sleep 16
.Lattn_nosleep:
	s_cbranch_vccnz .LBB0_366
	s_and_b64 vcc, exec, s[18:19]
	s_and_b32 s78, s69, 1
	s_cbranch_vccnz .LBB0_363
	v_ashrrev_i32_e32 v131, 3, v130
	v_add_u32_e32 v132, 0xffffff00, v131
	v_add_u32_e32 v128, s83, v132
	v_lshrrev_b32_e32 v133, 1, v131
	v_ashrrev_i32_e32 v129, 31, v128
	s_lshl_b32 s50, s78, 16
	v_lshlrev_b64 v[128:129], 15, v[128:129]
	v_bitop3_b32 v133, v133, 7, v130 bitop3:0x48
	s_add_i32 s76, s50, 0
	v_lshl_or_b32 v128, v133, 4, v128
	v_lshl_add_u64 v[128:129], s[72:73], 0, v[128:129]
	s_add_i32 m0, s76, s84
	s_nop 0
	global_load_lds_dwordx4 v[128:129], off
	v_add_u32_e32 v128, s85, v132
	v_lshrrev_b32_e32 v133, 1, v128
	v_add_u32_e32 v128, s88, v131
	v_ashrrev_i32_e32 v129, 31, v128
	v_lshlrev_b64 v[128:129], 15, v[128:129]
	v_bitop3_b32 v133, v133, 7, v130 bitop3:0x48
	v_lshl_or_b32 v128, v133, 4, v128
	v_lshl_add_u64 v[128:129], s[72:73], 0, v[128:129]
	s_add_i32 m0, s76, s86
	s_nop 0
	global_load_lds_dwordx4 v[128:129], off
	v_add_u32_e32 v128, s87, v132
	v_lshrrev_b32_e32 v133, 1, v128
	v_add_u32_e32 v128, s43, v131
	v_ashrrev_i32_e32 v129, 31, v128
	v_lshlrev_b64 v[128:129], 15, v[128:129]
	v_bitop3_b32 v133, v133, 7, v130 bitop3:0x48
	v_lshl_or_b32 v128, v133, 4, v128
	v_lshl_add_u64 v[128:129], s[72:73], 0, v[128:129]
	s_add_i32 m0, s76, s93
	s_nop 0
	global_load_lds_dwordx4 v[128:129], off
	v_add_u32_e32 v128, s94, v132
	v_lshrrev_b32_e32 v133, 1, v128
	v_add_u32_e32 v128, s42, v131
	v_ashrrev_i32_e32 v129, 31, v128
	v_lshlrev_b64 v[128:129], 15, v[128:129]
	v_bitop3_b32 v133, v133, 7, v130 bitop3:0x48
	v_lshl_or_b32 v128, v133, 4, v128
	v_lshl_add_u64 v[128:129], s[72:73], 0, v[128:129]
	s_add_i32 m0, s76, s95
	s_nop 0
	global_load_lds_dwordx4 v[128:129], off
	v_add_u32_e32 v128, s96, v132
	v_lshrrev_b32_e32 v133, 1, v128
	v_add_u32_e32 v128, s41, v131
	v_ashrrev_i32_e32 v129, 31, v128
	v_lshlrev_b64 v[128:129], 15, v[128:129]
	v_bitop3_b32 v133, v133, 7, v130 bitop3:0x48
	v_lshl_or_b32 v128, v133, 4, v128
	v_lshl_add_u64 v[128:129], s[72:73], 0, v[128:129]
	s_add_i32 m0, s76, s97
	s_nop 0
	global_load_lds_dwordx4 v[128:129], off
	v_add_u32_e32 v128, s89, v132
	v_lshrrev_b32_e32 v133, 1, v128
	v_add_u32_e32 v128, s40, v131
	v_ashrrev_i32_e32 v129, 31, v128
	v_lshlrev_b64 v[128:129], 15, v[128:129]
	v_bitop3_b32 v133, v133, 7, v130 bitop3:0x48
	v_lshl_or_b32 v128, v133, 4, v128
	v_lshl_add_u64 v[128:129], s[72:73], 0, v[128:129]
	s_add_i32 m0, s76, s34
	s_nop 0
	global_load_lds_dwordx4 v[128:129], off
	v_add_u32_e32 v128, s35, v132
	v_lshrrev_b32_e32 v133, 1, v128
	v_add_u32_e32 v128, s7, v131
	v_ashrrev_i32_e32 v129, 31, v128
	v_lshlrev_b64 v[128:129], 15, v[128:129]
	v_bitop3_b32 v131, v133, 7, v130 bitop3:0x48
	v_lshl_or_b32 v128, v131, 4, v128
	v_lshl_add_u64 v[128:129], s[72:73], 0, v[128:129]
	s_add_i32 m0, s76, s44
	s_nop 0
	global_load_lds_dwordx4 v[128:129], off
	v_add_u32_e32 v128, s45, v132
	v_lshrrev_b32_e32 v129, 1, v128
	s_cbranch_execz .LBB0_364
	s_mov_b32 vcc_lo, 56
	s_mov_b64 s[76:77], 15
	s_mov_b64 s[78:79], s[72:73]
	s_branch .LBB0_365
